# previous plus lane-linear layout of the f32 running-sum scratch of the branch GEMM (1 KiB contiguous per wave load/store instead of 16 rows x 64 B)
# speedup vs baseline: 1.0406x; 1.0063x over previous
.LBB9_100:
	v_mov_b32_e32 v42, v191
	v_mov_b32_e32 v148, v190
	s_lshl_b32 s6, s4, 8
	s_or_b32 s6, s6, s35
	v_lshlrev_b32_e32 v149, 3, v42
	v_add_u32_e32 v146, s6, v149
	v_ashrrev_i32_e32 v147, 31, v146
	v_add_u32_e32 v184, s38, v148
	v_lshl_add_u64 v[46:47], v[146:147], 2, s[16:17]
	v_ashrrev_i32_e32 v185, 31, v184
	global_load_dwordx4 v[50:53], v[46:47], off offset:16
	global_load_dwordx4 v[58:61], v[46:47], off
	global_load_dwordx4 v[42:45], v[46:47], off offset:528
	s_nop 0
	global_load_dwordx4 v[46:49], v[46:47], off offset:512
	v_lshl_add_u64 v[180:181], v[146:147], 1, s[86:87]
	v_lshlrev_b64 v[146:147], 13, v[184:185]
	v_lshl_add_u64 v[146:147], v[180:181], 0, v[146:147]
	global_load_dwordx4 v[162:165], v[146:147], off
	s_ashr_i32 s4, s4, 2
	v_add_u32_e32 v182, s39, v149
	v_ashrrev_i32_e32 v183, 31, v182
	v_lshrrev_b32_e32 v211, 8, v184
	v_lshrrev_b32_e32 v210, 8, v182
	v_lshl_add_u32 v211, v211, 2, v210
	v_bfe_u32 v210, v184, 6, 1
	v_lshl_add_u32 v211, v211, 1, v210
	v_bfe_u32 v210, v182, 5, 2
	v_lshl_add_u32 v211, v211, 2, v210
	v_lshlrev_b32_e32 v211, 15, v211
	v_lshl_add_u32 v211, v244, 4, v211
	s_cmp_lt_i32 s4, 1
	v_lshlrev_b64 v[148:149], 10, v[184:185]
	s_cselect_b64 s[8:9], -1, 0
	v_lshl_add_u64 v[188:189], v[148:149], 0, v[182:183]
	v_mov_b32_e32 v186, v211
	s_and_b64 vcc, exec, s[8:9]
	s_cbranch_vccnz .LBB9_102
	global_load_dwordx4 v[158:161], v186, s[18:19] offset:1024
	global_load_dwordx4 v[166:169], v186, s[18:19]
	s_branch .LBB9_103

.LBB9_105:
	s_andn2_b64 vcc, exec, s[8:9]
	s_cbranch_vccnz .LBB9_107
	global_load_dwordx4 v[150:153], v186, s[18:19] offset:3072
	global_load_dwordx4 v[154:157], v186, s[18:19] offset:2048
	s_branch .LBB9_108

.LBB9_110:
	s_andn2_b64 vcc, exec, s[8:9]
	s_cbranch_vccnz .LBB9_112
	global_store_dwordx4 v186, v[142:145], s[18:19]
	global_store_dwordx4 v186, v[138:141], s[18:19] offset:1024

.LBB9_114:
	s_andn2_b64 vcc, exec, s[28:29]
	s_cbranch_vccnz .LBB9_116
	global_store_dwordx4 v186, v[134:137], s[18:19] offset:2048
	global_store_dwordx4 v186, v[130:133], s[18:19] offset:3072

.LBB9_118:
	v_lshlrev_b64 v[132:133], 10, v[132:133]
	v_lshl_add_u64 v[156:157], v[132:133], 0, v[182:183]
	v_add_u32_e32 v154, 0x1000, v211
	v_mov_b32_e32 v142, 0
	s_andn2_b64 vcc, exec, s[28:29]
	v_mov_b32_e32 v143, 0
	v_mov_b32_e32 v144, 0
	v_mov_b32_e32 v145, 0
	v_mov_b32_e32 v150, 0
	v_mov_b32_e32 v151, 0
	v_mov_b32_e32 v152, 0
	v_mov_b32_e32 v153, 0
	s_cbranch_vccnz .LBB9_120
	global_load_dwordx4 v[142:145], v154, s[18:19] offset:1024
	global_load_dwordx4 v[150:153], v154, s[18:19]

.LBB9_122:
	v_mov_b32_e32 v130, 0
	s_andn2_b64 vcc, exec, s[28:29]
	v_mov_b32_e32 v131, 0
	v_mov_b32_e32 v132, 0
	v_mov_b32_e32 v133, 0
	v_mov_b32_e32 v138, 0
	v_mov_b32_e32 v139, 0
	v_mov_b32_e32 v140, 0
	v_mov_b32_e32 v141, 0
	s_cbranch_vccnz .LBB9_124
	global_load_dwordx4 v[130:133], v154, s[18:19] offset:3072
	global_load_dwordx4 v[138:141], v154, s[18:19] offset:2048

.LBB9_126:
	s_andn2_b64 vcc, exec, s[28:29]
	s_cbranch_vccnz .LBB9_128
	global_store_dwordx4 v154, v[126:129], s[18:19]
	global_store_dwordx4 v154, v[122:125], s[18:19] offset:1024

.LBB9_130:
	s_andn2_b64 vcc, exec, s[28:29]
	s_cbranch_vccnz .LBB9_132
	global_store_dwordx4 v154, v[118:121], s[18:19] offset:2048
	global_store_dwordx4 v154, v[114:117], s[18:19] offset:3072

.LBB9_134:
	v_lshlrev_b64 v[116:117], 10, v[116:117]
	v_lshl_add_u64 v[140:141], v[116:117], 0, v[182:183]
	v_add_u32_e32 v138, 0x2000, v211
	v_mov_b32_e32 v126, 0
	s_andn2_b64 vcc, exec, s[28:29]
	v_mov_b32_e32 v127, 0
	v_mov_b32_e32 v128, 0
	v_mov_b32_e32 v129, 0
	v_mov_b32_e32 v134, 0
	v_mov_b32_e32 v135, 0
	v_mov_b32_e32 v136, 0
	v_mov_b32_e32 v137, 0
	s_cbranch_vccnz .LBB9_136
	global_load_dwordx4 v[126:129], v138, s[18:19] offset:1024
	global_load_dwordx4 v[134:137], v138, s[18:19]

.LBB9_138:
	v_mov_b32_e32 v114, 0
	s_andn2_b64 vcc, exec, s[28:29]
	v_mov_b32_e32 v115, 0
	v_mov_b32_e32 v116, 0
	v_mov_b32_e32 v117, 0
	v_mov_b32_e32 v122, 0
	v_mov_b32_e32 v123, 0
	v_mov_b32_e32 v124, 0
	v_mov_b32_e32 v125, 0
	s_cbranch_vccnz .LBB9_140
	global_load_dwordx4 v[114:117], v138, s[18:19] offset:3072
	global_load_dwordx4 v[122:125], v138, s[18:19] offset:2048

.LBB9_150:
	v_lshlrev_b64 v[150:151], 10, v[150:151]
	v_lshl_add_u64 v[194:195], v[150:151], 0, v[182:183]
	v_add_u32_e32 v168, 0x3000, v211
	v_mov_b32_e32 v160, 0
	s_andn2_b64 vcc, exec, s[28:29]
	v_mov_b32_e32 v161, 0
	v_mov_b32_e32 v162, 0
	v_mov_b32_e32 v163, 0
	v_mov_b32_e32 v186, 0
	v_mov_b32_e32 v187, 0
	v_mov_b32_e32 v188, 0
	v_mov_b32_e32 v189, 0
	s_cbranch_vccnz .LBB9_152
	global_load_dwordx4 v[160:163], v168, s[18:19] offset:1024
	global_load_dwordx4 v[186:189], v168, s[18:19]

.LBB9_154:
	v_mov_b32_e32 v148, 0
	s_andn2_b64 vcc, exec, s[28:29]
	v_mov_b32_e32 v149, 0
	v_mov_b32_e32 v150, 0
	v_mov_b32_e32 v151, 0
	v_mov_b32_e32 v156, 0
	v_mov_b32_e32 v157, 0
	v_mov_b32_e32 v158, 0
	v_mov_b32_e32 v159, 0
	s_cbranch_vccnz .LBB9_156
	global_load_dwordx4 v[148:151], v168, s[18:19] offset:3072
	global_load_dwordx4 v[156:159], v168, s[18:19] offset:2048

.LBB9_142:
	s_andn2_b64 vcc, exec, s[28:29]
	s_cbranch_vccnz .LBB9_144
	global_store_dwordx4 v138, v[110:113], s[18:19]
	global_store_dwordx4 v138, v[106:109], s[18:19] offset:1024

.LBB9_146:
	s_andn2_b64 vcc, exec, s[28:29]
	s_cbranch_vccnz .LBB9_148
	global_store_dwordx4 v138, v[102:105], s[18:19] offset:2048
	global_store_dwordx4 v138, v[98:101], s[18:19] offset:3072

.LBB9_158:
	s_andn2_b64 vcc, exec, s[28:29]
	s_cbranch_vccnz .LBB9_160
	global_store_dwordx4 v168, v[94:97], s[18:19]
	global_store_dwordx4 v168, v[90:93], s[18:19] offset:1024

.LBB9_162:
	s_andn2_b64 vcc, exec, s[28:29]
	s_cbranch_vccnz .LBB9_164
	global_store_dwordx4 v168, v[86:89], s[18:19] offset:2048
	global_store_dwordx4 v168, v[82:85], s[18:19] offset:3072

.LBB9_166:
	v_lshlrev_b64 v[84:85], 10, v[84:85]
	v_lshl_add_u64 v[108:109], v[84:85], 0, v[182:183]
	v_add_u32_e32 v106, 0x4000, v211
	v_mov_b32_e32 v94, 0
	s_andn2_b64 vcc, exec, s[28:29]
	v_mov_b32_e32 v95, 0
	v_mov_b32_e32 v96, 0
	v_mov_b32_e32 v97, 0
	v_mov_b32_e32 v102, 0
	v_mov_b32_e32 v103, 0
	v_mov_b32_e32 v104, 0
	v_mov_b32_e32 v105, 0
	s_cbranch_vccnz .LBB9_168
	global_load_dwordx4 v[94:97], v106, s[18:19] offset:1024
	global_load_dwordx4 v[102:105], v106, s[18:19]

.LBB9_170:
	v_mov_b32_e32 v82, 0
	s_andn2_b64 vcc, exec, s[28:29]
	v_mov_b32_e32 v83, 0
	v_mov_b32_e32 v84, 0
	v_mov_b32_e32 v85, 0
	v_mov_b32_e32 v90, 0
	v_mov_b32_e32 v91, 0
	v_mov_b32_e32 v92, 0
	v_mov_b32_e32 v93, 0
	s_cbranch_vccnz .LBB9_172
	global_load_dwordx4 v[82:85], v106, s[18:19] offset:3072
	global_load_dwordx4 v[90:93], v106, s[18:19] offset:2048

.LBB9_182:
	v_lshlrev_b64 v[118:119], 10, v[118:119]
	v_lshl_add_u64 v[142:143], v[118:119], 0, v[182:183]
	v_add_u32_e32 v140, 0x5000, v211
	v_mov_b32_e32 v128, 0
	s_andn2_b64 vcc, exec, s[28:29]
	v_mov_b32_e32 v129, 0
	v_mov_b32_e32 v130, 0
	v_mov_b32_e32 v131, 0
	v_mov_b32_e32 v136, 0
	v_mov_b32_e32 v137, 0
	v_mov_b32_e32 v138, 0
	v_mov_b32_e32 v139, 0
	s_cbranch_vccnz .LBB9_184
	global_load_dwordx4 v[128:131], v140, s[18:19] offset:1024
	global_load_dwordx4 v[136:139], v140, s[18:19]

.LBB9_186:
	v_mov_b32_e32 v116, 0
	s_andn2_b64 vcc, exec, s[28:29]
	v_mov_b32_e32 v117, 0
	v_mov_b32_e32 v118, 0
	v_mov_b32_e32 v119, 0
	v_mov_b32_e32 v124, 0
	v_mov_b32_e32 v125, 0
	v_mov_b32_e32 v126, 0
	v_mov_b32_e32 v127, 0
	s_cbranch_vccnz .LBB9_188
	global_load_dwordx4 v[116:119], v140, s[18:19] offset:3072
	global_load_dwordx4 v[124:127], v140, s[18:19] offset:2048

.LBB9_174:
	s_andn2_b64 vcc, exec, s[28:29]
	s_cbranch_vccnz .LBB9_176
	global_store_dwordx4 v106, v[78:81], s[18:19]
	global_store_dwordx4 v106, v[74:77], s[18:19] offset:1024

.LBB9_178:
	s_andn2_b64 vcc, exec, s[28:29]
	s_cbranch_vccnz .LBB9_180
	global_store_dwordx4 v106, v[70:73], s[18:19] offset:2048
	global_store_dwordx4 v106, v[66:69], s[18:19] offset:3072

.LBB9_190:
	s_andn2_b64 vcc, exec, s[28:29]
	s_cbranch_vccnz .LBB9_192
	global_store_dwordx4 v140, v[62:65], s[18:19]
	global_store_dwordx4 v140, v[54:57], s[18:19] offset:1024

.LBB9_194:
	s_andn2_b64 vcc, exec, s[28:29]
	s_cbranch_vccnz .LBB9_196
	global_store_dwordx4 v140, v[38:41], s[18:19] offset:2048
	global_store_dwordx4 v140, v[34:37], s[18:19] offset:3072

.LBB9_198:
	v_lshlrev_b64 v[36:37], 10, v[36:37]
	v_lshl_add_u64 v[76:77], v[36:37], 0, v[182:183]
	v_add_u32_e32 v74, 0x6000, v211
	v_mov_b32_e32 v62, 0
	s_andn2_b64 vcc, exec, s[28:29]
	v_mov_b32_e32 v63, 0
	v_mov_b32_e32 v64, 0
	v_mov_b32_e32 v65, 0
	v_mov_b32_e32 v70, 0
	v_mov_b32_e32 v71, 0
	v_mov_b32_e32 v72, 0
	v_mov_b32_e32 v73, 0
	s_cbranch_vccnz .LBB9_200
	global_load_dwordx4 v[62:65], v74, s[18:19] offset:1024
	global_load_dwordx4 v[70:73], v74, s[18:19]

.LBB9_202:
	v_mov_b32_e32 v34, 0
	s_andn2_b64 vcc, exec, s[28:29]
	v_mov_b32_e32 v35, 0
	v_mov_b32_e32 v36, 0
	v_mov_b32_e32 v37, 0
	v_mov_b32_e32 v54, 0
	v_mov_b32_e32 v55, 0
	v_mov_b32_e32 v56, 0
	v_mov_b32_e32 v57, 0
	s_cbranch_vccnz .LBB9_204
	global_load_dwordx4 v[34:37], v74, s[18:19] offset:3072
	global_load_dwordx4 v[54:57], v74, s[18:19] offset:2048

.LBB9_214:
	v_lshlrev_b64 v[86:87], 10, v[86:87]
	v_lshl_add_u64 v[110:111], v[86:87], 0, v[182:183]
	v_add_u32_e32 v108, 0x7000, v211
	v_mov_b32_e32 v96, 0
	s_andn2_b64 vcc, exec, s[28:29]
	v_mov_b32_e32 v97, 0
	v_mov_b32_e32 v98, 0
	v_mov_b32_e32 v99, 0
	v_mov_b32_e32 v104, 0
	v_mov_b32_e32 v105, 0
	v_mov_b32_e32 v106, 0
	v_mov_b32_e32 v107, 0
	s_cbranch_vccnz .LBB9_216
	global_load_dwordx4 v[96:99], v108, s[18:19] offset:1024
	global_load_dwordx4 v[104:107], v108, s[18:19]

.LBB9_218:
	v_mov_b32_e32 v84, 0
	s_andn2_b64 vcc, exec, s[6:7]
	v_mov_b32_e32 v85, 0
	v_mov_b32_e32 v86, 0
	v_mov_b32_e32 v87, 0
	v_mov_b32_e32 v92, 0
	v_mov_b32_e32 v93, 0
	v_mov_b32_e32 v94, 0
	v_mov_b32_e32 v95, 0
	s_cbranch_vccnz .LBB9_220
	global_load_dwordx4 v[84:87], v108, s[18:19] offset:3072
	global_load_dwordx4 v[92:95], v108, s[18:19] offset:2048

.LBB9_206:
	s_andn2_b64 vcc, exec, s[28:29]
	s_cbranch_vccnz .LBB9_208
	global_store_dwordx4 v74, v[30:33], s[18:19]
	global_store_dwordx4 v74, v[26:29], s[18:19] offset:1024

.LBB9_210:
	s_andn2_b64 vcc, exec, s[28:29]
	s_cbranch_vccnz .LBB9_212
	global_store_dwordx4 v74, v[22:25], s[18:19] offset:2048
	global_store_dwordx4 v74, v[18:21], s[18:19] offset:3072

.LBB9_222:
	s_andn2_b64 vcc, exec, s[6:7]
	s_cbranch_vccnz .LBB9_224
	global_store_dwordx4 v108, v[14:17], s[18:19]
	global_store_dwordx4 v108, v[10:13], s[18:19] offset:1024

.LBB9_226:
	s_andn2_b64 vcc, exec, s[6:7]
	s_cbranch_vccnz .LBB9_228
	global_store_dwordx4 v108, v[6:9], s[18:19] offset:2048
	global_store_dwordx4 v108, v[2:5], s[18:19] offset:3072
